# GLA step-loop prefetch addresses through SGPR base + 32-bit VGPR offset (7 instead of 13 VALU per half step, no 64-bit address math); same addresses and clamps
# baseline (speedup 1.0000x reference)
.LBB0_229:
	s_or_b64 exec, exec, s[26:27]
	s_and_b32 s10, s42, 1
	s_bfe_u32 s28, s42, 0x20001
	s_cmp_eq_u32 s10, 0
	s_cselect_b64 s[0:1], -1, 0
	s_bfe_u32 s31, s42, 0x10003
	s_ashr_i32 s26, s42, 4
	s_lshl_b32 s29, s28, 23
	s_add_u32 s30, s20, s29
	s_addc_u32 s43, s21, 0
	s_ashr_i32 s27, s26, 31
	s_lshl_b64 s[4:5], s[26:27], 19
	s_add_u32 s44, s30, s4
	s_addc_u32 s45, s43, s5
	s_lshl_b32 s27, s28, 24
	s_lshl_b32 s30, s31, 23
	s_or_b32 s27, s30, s27
	s_add_u32 s27, s20, s27
	s_addc_u32 s30, s21, 0
	v_lshl_add_u64 v[72:73], s[44:45], 0, v[68:69]
	s_mov_b64 s[94:95], s[44:45]
	s_add_u32 s96, s44, s18
	s_addc_u32 s97, s45, s19
	s_add_u32 s44, s27, s4
	s_addc_u32 s45, s30, s5
	s_add_u32 s98, s44, s22
	s_addc_u32 s99, s45, s23
	s_lshl_b32 s10, s10, 25
	s_or_b32 s10, s10, s29
	s_add_u32 s10, s36, s10
	s_addc_u32 s27, s37, 0
	s_add_u32 s4, s10, s4
	v_cndmask_b32_e64 v10, v107, v106, s[0:1]
	s_addc_u32 s5, s27, s5
	v_lshlrev_b32_e32 v10, 1, v10
	v_mov_b32_e32 v11, v69
	v_lshl_add_u64 v[74:75], s[4:5], 0, v[68:69]
	s_mov_b64 s[100:101], s[4:5]
	v_lshl_add_u64 v[12:13], v[72:73], 0, v[10:11]
	global_load_dwordx4 v[34:37], v[12:13], off
	v_lshl_add_u64 v[12:13], v[74:75], 0, v[10:11]
	global_load_dwordx4 v[38:41], v[12:13], off
	v_lshl_add_u64 v[76:77], v[72:73], 0, s[18:19]
	v_lshl_add_u64 v[12:13], v[76:77], 0, v[10:11]
	global_load_dwordx4 v[44:47], v[12:13], off
	v_lshl_add_u64 v[12:13], s[44:45], 0, v[68:69]
	v_lshl_add_u64 v[78:79], v[12:13], 0, s[22:23]
	v_lshl_add_u64 v[10:11], v[78:79], 0, v[10:11]
	global_load_dwordx4 v[26:29], v[10:11], off
	v_cndmask_b32_e64 v10, v83, v82, s[0:1]
	v_cndmask_b32_e64 v42, v85, v84, s[0:1]
	v_mov_b32_e32 v15, v69
	v_mov_b32_e32 v17, v69
	v_lshlrev_b32_e32 v14, 7, v10
	v_lshlrev_b32_e32 v16, 7, v42
	v_lshl_add_u64 v[18:19], v[72:73], 0, v[14:15]
	v_lshl_add_u64 v[10:11], v[76:77], 0, v[14:15]
	v_lshl_add_u64 v[12:13], v[78:79], 0, v[14:15]
	v_lshl_add_u64 v[14:15], v[74:75], 0, v[14:15]
	v_lshl_add_u64 v[16:17], v[74:75], 0, v[16:17]
	global_load_dwordx4 v[22:25], v[10:11], off
	s_nop 0
	global_load_dwordx4 v[10:13], v[12:13], off
	s_nop 0
	global_load_dwordx4 v[30:33], v[14:15], off
	s_nop 0
	global_load_dwordx4 v[18:21], v[18:19], off
	s_nop 0
	global_load_dwordx4 v[14:17], v[16:17], off
	v_add_u32_e32 v123, v86, v87
	v_add_u32_e32 v124, v86, v88
	s_waitcnt vmcnt(8)
	v_lshlrev_b32_e32 v56, 16, v34
	v_and_b32_e32 v57, 0xffff0000, v34
	s_waitcnt vmcnt(7)
	ds_write_b128 v111, v[38:41] offset:36864
	s_waitcnt lgkmcnt(0)
	s_barrier
	ds_read_b64_tr_b16 v[40:41], v112 offset:37440
	ds_read_b64_tr_b16 v[38:39], v112 offset:36864
	ds_read_b64_tr_b16 v[50:51], v112 offset:37472
	ds_read_b64_tr_b16 v[48:49], v112 offset:36896
	ds_read_b64_tr_b16 v[52:53], v112 offset:41472
	ds_read_b64_tr_b16 v[54:55], v112 offset:42048
	s_waitcnt lgkmcnt(4)
	v_mfma_f32_16x16x32_bf16 v[38:41], v[38:41], v[2:5], 0
	ds_read_b64_tr_b16 v[128:129], v112 offset:42080
	ds_read_b64_tr_b16 v[126:127], v112 offset:41504
	v_lshlrev_b32_e32 v80, 16, v35
	v_and_b32_e32 v81, 0xffff0000, v35
	s_waitcnt lgkmcnt(4)
	v_mfma_f32_16x16x32_bf16 v[48:51], v[48:51], v[2:5], 0
	v_lshlrev_b32_e32 v130, 16, v36
	v_and_b32_e32 v131, 0xffff0000, v36
	v_lshlrev_b32_e32 v132, 16, v37
	v_and_b32_e32 v133, 0xffff0000, v37
	s_waitcnt lgkmcnt(2)
	v_mfma_f32_16x16x32_bf16 v[34:37], v[52:55], v[6:9], v[38:41]
	s_waitcnt vmcnt(6)
	v_lshlrev_b32_e32 v134, 16, v44
	v_and_b32_e32 v135, 0xffff0000, v44
	v_lshlrev_b32_e32 v44, 16, v45
	s_waitcnt lgkmcnt(0)
	v_mfma_f32_16x16x32_bf16 v[38:41], v[126:129], v[6:9], v[48:51]
	s_nop 1
	ds_write_b128 v123, v[34:37]
	s_nop 4
	ds_write_b128 v124, v[38:41]
	s_waitcnt lgkmcnt(0)
	s_barrier
	ds_read_b128 v[34:37], v113
	ds_read_b128 v[38:41], v113 offset:16
	v_and_b32_e32 v45, 0xffff0000, v45
	v_lshlrev_b32_e32 v52, 16, v46
	v_and_b32_e32 v53, 0xffff0000, v46
	s_waitcnt lgkmcnt(1)
	v_exp_f32_e64 v48, -v34
	v_exp_f32_e64 v49, -v35
	v_exp_f32_e64 v50, -v36
	v_exp_f32_e64 v51, -v37
	s_waitcnt lgkmcnt(0)
	v_exp_f32_e64 v54, -v38
	v_exp_f32_e64 v55, -v39
	v_exp_f32_e32 v34, v34
	v_exp_f32_e32 v35, v35
	v_exp_f32_e32 v36, v36
	v_exp_f32_e32 v37, v37
	v_exp_f32_e32 v38, v38
	v_exp_f32_e32 v39, v39
	v_exp_f32_e64 v126, -v40
	v_exp_f32_e64 v127, -v41
	v_exp_f32_e32 v40, v40
	v_exp_f32_e32 v41, v41
	v_lshlrev_b32_e32 v46, 16, v47
	v_and_b32_e32 v47, 0xffff0000, v47
	v_pk_mul_f32 v[48:49], v[48:49], v[134:135]
	v_pk_mul_f32 v[50:51], v[50:51], v[44:45]
	v_pk_mul_f32 v[52:53], v[54:55], v[52:53]
	v_pk_mul_f32 v[56:57], v[34:35], v[56:57]
	v_pk_mul_f32 v[80:81], v[36:37], v[80:81]
	v_pk_mul_f32 v[54:55], v[38:39], v[130:131]
	v_pk_mul_f32 v[126:127], v[126:127], v[46:47]
	v_cvt_pk_bf16_f32 v48, v48, v49
	v_cvt_pk_bf16_f32 v49, v50, v51
	v_cvt_pk_bf16_f32 v50, v52, v53
	v_pk_mul_f32 v[52:53], v[40:41], v[132:133]
	v_cvt_pk_bf16_f32 v44, v56, v57
	v_cvt_pk_bf16_f32 v45, v80, v81
	v_cvt_pk_bf16_f32 v46, v54, v55
	v_cvt_pk_bf16_f32 v47, v52, v53
	v_cvt_pk_bf16_f32 v51, v126, v127
	v_add_u32_e32 v126, 0, v89
	ds_write_b128 v111, v[44:47]
	ds_write_b128 v111, v[48:51] offset:55296
	s_and_saveexec_b64 s[4:5], vcc
	s_cbranch_execz .LBB0_231
	ds_write_b128 v126, v[34:37] offset:46080
	ds_write_b128 v126, v[38:41] offset:46096

.LBB0_232:
	s_or_b64 exec, exec, s[26:27]
	s_waitcnt vmcnt(7)
	ds_write_b128 v114, v[26:29]
	s_waitcnt vmcnt(6)
	ds_write_b128 v111, v[30:33] offset:36864
	s_min_u32 s26, s31, 59
	global_load_dwordx4 v[34:37], v54, s[94:95]
	global_load_dwordx4 v[38:41], v54, s[96:97]
	v_lshl_add_u32 v28, s26, 6, v98
	v_sub_u32_e32 v29, 0xfff, v28
	v_cndmask_b32_e64 v28, v29, v28, s[0:1]
	v_lshl_add_u32 v30, v28, 7, v68
	global_load_dwordx4 v[26:29], v54, s[98:99]
	s_nop 0
	global_load_dwordx4 v[30:33], v30, s[100:101]
	s_waitcnt lgkmcnt(0)
	s_barrier
	ds_read_b128 v[50:53], v95 offset:55296
	ds_read_b128 v[54:57], v125
	ds_read_b128 v[132:135], v125 offset:64
	ds_read_b128 v[136:139], v95 offset:55360
	ds_read_b128 v[140:143], v95 offset:57600
	ds_read_b128 v[144:147], v95 offset:57664
	s_waitcnt lgkmcnt(4)
	v_mfma_f32_16x16x32_bf16 v[50:53], v[50:53], v[54:57], 0
	ds_read_b128 v[150:153], v95 offset:27648
	ds_read_b128 v[154:157], v95 offset:27712
	ds_read_b128 v[158:161], v95 offset:29952
	ds_read_b128 v[162:165], v95 offset:30016
	s_addk_i32 s29, 0x80
	s_waitcnt lgkmcnt(5)
	v_mfma_f32_16x16x32_bf16 v[140:143], v[140:143], v[54:57], 0
	v_add_u32_e32 v130, 0xffffff80, v130
	s_cmp_gt_u32 s31, 60
	v_add_u32_e32 v129, 0xffffff80, v129
	v_mfma_f32_16x16x32_bf16 v[136:139], v[136:139], v[132:135], v[50:53]
	s_waitcnt lgkmcnt(4)
	v_mfma_f32_16x16x32_bf16 v[140:143], v[144:147], v[132:135], v[140:143]
	s_waitcnt lgkmcnt(3)
	v_mfma_f32_16x16x32_bf16 v[150:153], v[150:153], v[54:57], 0
	s_nop 3
	v_mul_f32_e64 v138, v60, v138
	v_mul_f32_e64 v139, v61, v139
	v_pk_mul_f32 v[136:137], v[58:59], v[136:137]
	v_pk_mul_f32 v[142:143], v[64:65], v[142:143]
	s_waitcnt lgkmcnt(1)
	v_mfma_f32_16x16x32_bf16 v[54:57], v[158:161], v[54:57], 0
	v_mul_f32_e64 v140, v62, v140
	v_mul_f32_e64 v141, v63, v141
	v_cvt_pk_bf16_f32 v136, v136, v137
	v_cvt_pk_bf16_f32 v137, v138, v139
	ds_write_b64 v115, v[136:137] offset:18432
	v_cvt_pk_bf16_f32 v136, v140, v141
	v_cvt_pk_bf16_f32 v137, v142, v143
	ds_write_b64 v116, v[136:137] offset:18432
	ds_read_b64_tr_b16 v[138:139], v112 offset:37440
	ds_read_b64_tr_b16 v[136:137], v112 offset:36864
	v_mfma_f32_16x16x32_bf16 v[50:53], v[154:157], v[132:135], v[150:153]
	s_waitcnt lgkmcnt(4)
	v_mfma_f32_16x16x32_bf16 v[54:57], v[162:165], v[132:135], v[54:57]
	ds_read_b64_tr_b16 v[134:135], v112 offset:37472
	ds_read_b64_tr_b16 v[132:133], v112 offset:36896
	ds_read_b64_tr_b16 v[140:141], v112 offset:41472
	ds_read_b64_tr_b16 v[142:143], v112 offset:42048
	ds_read_b64_tr_b16 v[146:147], v112 offset:42080
	ds_read_b64_tr_b16 v[144:145], v112 offset:41504
	s_waitcnt lgkmcnt(6)
	v_mfma_f32_16x16x32_bf16 v[136:139], v[136:139], v[2:5], 0
	s_waitcnt lgkmcnt(4)
	v_mfma_f32_16x16x32_bf16 v[132:135], v[132:135], v[2:5], 0
	s_waitcnt lgkmcnt(2)
	v_mfma_f32_16x16x32_bf16 v[136:139], v[140:143], v[6:9], v[136:139]
	s_waitcnt lgkmcnt(0)
	v_mfma_f32_16x16x32_bf16 v[132:135], v[144:147], v[6:9], v[132:135]
	s_nop 5
	ds_write_b128 v127, v[136:139]
	s_nop 0
	ds_write_b128 v128, v[132:135]
	s_waitcnt lgkmcnt(0)
	s_barrier
	s_cbranch_scc1 .LBB0_237

.LBB0_235:
	s_or_b64 exec, exec, s[26:27]
	ds_write_b128 v121, v[10:13]
	s_waitcnt vmcnt(5)
	ds_write_b128 v111, v[14:17] offset:36864
	v_add_u32_e32 v10, s29, v90
	v_cndmask_b32_e64 v10, v130, v10, s[0:1]
	s_add_i32 s31, s31, 2
	v_lshl_add_u32 v14, v10, 7, v68
	s_min_u32 s26, s31, 60
	global_load_dwordx4 v[18:21], v14, s[94:95]
	global_load_dwordx4 v[22:25], v14, s[96:97]
	v_lshl_add_u32 v12, s26, 6, v90
	v_sub_u32_e32 v13, 0xfff, v12
	v_cndmask_b32_e64 v12, v13, v12, s[0:1]
	v_lshl_add_u32 v54, v12, 7, v68
	global_load_dwordx4 v[10:13], v14, s[98:99]
	s_nop 0
	global_load_dwordx4 v[14:17], v54, s[100:101]
	s_waitcnt lgkmcnt(0)
	s_barrier
	ds_read_b128 v[50:53], v95 offset:64512
	ds_read_b128 v[132:135], v125
	ds_read_b128 v[136:139], v125 offset:64
	ds_read_b128 v[140:143], v95 offset:64576
	ds_read_b128 v[144:147], v102 offset:2304
	ds_read_b128 v[150:153], v102 offset:2368
	s_waitcnt lgkmcnt(4)
	v_mfma_f32_16x16x32_bf16 v[50:53], v[50:53], v[132:135], 0
	ds_read_b128 v[154:157], v95 offset:27648
	ds_read_b128 v[158:161], v95 offset:27712
	ds_read_b128 v[162:165], v95 offset:29952
	ds_read_b128 v[166:169], v95 offset:30016
	s_waitcnt lgkmcnt(5)
	v_mfma_f32_16x16x32_bf16 v[144:147], v[144:147], v[132:135], 0
	v_mfma_f32_16x16x32_bf16 v[50:53], v[140:143], v[136:139], v[50:53]
	s_waitcnt lgkmcnt(4)
	v_mfma_f32_16x16x32_bf16 v[140:143], v[150:153], v[136:139], v[144:147]
	s_waitcnt lgkmcnt(3)
	v_mfma_f32_16x16x32_bf16 v[154:157], v[154:157], v[132:135], 0
	s_nop 3
	v_mul_f32_e64 v52, v60, v52
	v_mul_f32_e64 v53, v61, v53
	v_pk_mul_f32 v[50:51], v[58:59], v[50:51]
	v_pk_mul_f32 v[142:143], v[64:65], v[142:143]
	s_waitcnt lgkmcnt(1)
	v_mfma_f32_16x16x32_bf16 v[132:135], v[162:165], v[132:135], 0
	v_mul_f32_e64 v140, v62, v140
	v_mul_f32_e64 v141, v63, v141
	v_cvt_pk_bf16_f32 v50, v50, v51
	v_cvt_pk_bf16_f32 v51, v52, v53
	ds_write_b64 v115, v[50:51] offset:18432
	v_cvt_pk_bf16_f32 v50, v140, v141
	v_cvt_pk_bf16_f32 v51, v142, v143
	ds_write_b64 v116, v[50:51] offset:18432
	ds_read_b64_tr_b16 v[52:53], v112 offset:37440
	ds_read_b64_tr_b16 v[50:51], v112 offset:36864
	v_mfma_f32_16x16x32_bf16 v[144:147], v[158:161], v[136:139], v[154:157]
	s_waitcnt lgkmcnt(4)
	v_mfma_f32_16x16x32_bf16 v[132:135], v[166:169], v[136:139], v[132:135]
	ds_read_b64_tr_b16 v[138:139], v112 offset:37472
	ds_read_b64_tr_b16 v[136:137], v112 offset:36896
	ds_read_b64_tr_b16 v[140:141], v112 offset:41472
	ds_read_b64_tr_b16 v[142:143], v112 offset:42048
	ds_read_b64_tr_b16 v[152:153], v112 offset:42080
	ds_read_b64_tr_b16 v[150:151], v112 offset:41504
	s_waitcnt lgkmcnt(6)
	v_mfma_f32_16x16x32_bf16 v[50:53], v[50:53], v[2:5], 0
	s_waitcnt lgkmcnt(4)
	v_mfma_f32_16x16x32_bf16 v[136:139], v[136:139], v[2:5], 0
	s_waitcnt lgkmcnt(2)
	v_mfma_f32_16x16x32_bf16 v[50:53], v[140:143], v[6:9], v[50:53]
	s_waitcnt lgkmcnt(0)
	v_mfma_f32_16x16x32_bf16 v[136:139], v[150:153], v[6:9], v[136:139]
	s_nop 5
	ds_write_b128 v123, v[50:53]
	s_nop 0
	ds_write_b128 v124, v[136:139]
	s_waitcnt lgkmcnt(0)
	s_barrier
	ds_read_b64_tr_b16 v[50:51], v122
	ds_read_b64_tr_b16 v[52:53], v122 offset:576
	ds_read_b64_tr_b16 v[138:139], v122 offset:608
	ds_read_b64_tr_b16 v[140:141], v122 offset:4608
	ds_read_b64_tr_b16 v[136:137], v122 offset:32
	ds_read_b128 v[150:153], v125 offset:18432
	ds_read_b128 v[154:157], v125 offset:18496
	ds_read_b128 v[158:161], v118 offset:46336
	ds_read_b64_tr_b16 v[142:143], v122 offset:5184
	s_waitcnt lgkmcnt(3)
	v_mfma_f32_16x16x32_bf16 v[144:147], v[50:53], v[150:153], v[144:147]
	v_mfma_f32_16x16x32_bf16 v[132:135], v[136:139], v[150:153], v[132:135]
	ds_read_b64_tr_b16 v[152:153], v122 offset:5216
	ds_read_b64_tr_b16 v[150:151], v122 offset:4640
	s_waitcnt lgkmcnt(2)
	v_mfma_f32_16x16x32_bf16 v[144:147], v[140:143], v[154:157], v[144:147]
	s_waitcnt lgkmcnt(0)
	v_mfma_f32_16x16x32_bf16 v[132:135], v[150:153], v[154:157], v[132:135]
	ds_read_b64_tr_b16 v[154:155], v101 offset:64512
	ds_read_b64_tr_b16 v[156:157], v101 offset:65088
	ds_read_b64_tr_b16 v[162:163], v105 offset:4608
	ds_read_b64_tr_b16 v[164:165], v105 offset:5184
	s_waitcnt lgkmcnt(2)
	v_mfma_f32_16x16x32_bf16 v[46:49], v[154:157], v[50:53], v[46:49]
	v_add_u32_e32 v50, 64, v56
	v_cndmask_b32_e64 v50, v129, v50, s[0:1]
	v_add_u32_e32 v50, s30, v50
	v_mfma_f32_16x16x32_bf16 v[42:45], v[154:157], v[136:139], v[42:45]
	v_ashrrev_i32_e32 v51, 31, v50
	v_lshlrev_b64 v[50:51], 10, v[50:51]
	v_lshl_add_u64 v[56:57], v[80:81], 0, v[50:51]
	s_waitcnt lgkmcnt(0)
	v_mfma_f32_16x16x32_bf16 v[46:49], v[162:165], v[140:143], v[46:49]
	v_cvt_pk_bf16_f32 v172, v144, v145
	v_cvt_pk_bf16_f32 v173, v146, v147
	s_nop 0
	v_mfma_f32_16x16x32_bf16 v[42:45], v[162:165], v[150:153], v[42:45]
	v_cvt_pk_bf16_f32 v174, v132, v133
	s_nop 2
	v_pk_mul_f32 v[48:49], v[160:161], v[48:49]
	v_pk_mul_f32 v[46:47], v[158:159], v[46:47]
	v_cvt_pk_bf16_f32 v51, v48, v49
	v_cvt_pk_bf16_f32 v50, v46, v47
	v_pk_mul_f32 v[44:45], v[160:161], v[44:45]
	v_pk_mul_f32 v[42:43], v[158:159], v[42:43]
	ds_write_b64 v131, v[50:51] offset:27648
	v_cvt_pk_bf16_f32 v50, v42, v43
	v_cvt_pk_bf16_f32 v51, v44, v45
	ds_write_b64 v119, v[50:51] offset:27648
	ds_read_b128 v[50:53], v113
	v_cvt_pk_bf16_f32 v175, v134, v135
	s_nop 1
	v_permlane16_swap_b32_e32 v172, v174
	v_permlane16_swap_b32_e32 v173, v175
	global_store_dwordx4 v[56:57], v[172:175], off
	ds_read_b128 v[132:135], v113 offset:16
	s_waitcnt vmcnt(8)
	v_lshlrev_b32_e32 v136, 16, v38
	s_waitcnt lgkmcnt(1)
	v_exp_f32_e64 v56, -v50
	v_exp_f32_e64 v57, -v51
	v_exp_f32_e32 v50, v50
	v_exp_f32_e32 v51, v51
	v_and_b32_e32 v137, 0xffff0000, v38
	v_pk_mul_f32 v[56:57], v[56:57], v[136:137]
	v_lshlrev_b32_e32 v136, 16, v34
	v_and_b32_e32 v137, 0xffff0000, v34
	v_pk_mul_f32 v[136:137], v[50:51], v[136:137]
	v_lshlrev_b32_e32 v38, 16, v39
	v_cvt_pk_bf16_f32 v34, v136, v137
	v_cvt_pk_bf16_f32 v136, v56, v57
	v_exp_f32_e64 v56, -v52
	v_exp_f32_e64 v57, -v53
	v_exp_f32_e32 v52, v52
	v_exp_f32_e32 v53, v53
	v_and_b32_e32 v39, 0xffff0000, v39
	v_pk_mul_f32 v[38:39], v[56:57], v[38:39]
	v_lshlrev_b32_e32 v56, 16, v35
	v_and_b32_e32 v57, 0xffff0000, v35
	v_pk_mul_f32 v[56:57], v[52:53], v[56:57]
	v_cvt_pk_bf16_f32 v137, v38, v39
	v_cvt_pk_bf16_f32 v35, v56, v57
	s_waitcnt lgkmcnt(0)
	v_exp_f32_e64 v56, -v132
	v_exp_f32_e64 v57, -v133
	v_exp_f32_e32 v38, v132
	v_exp_f32_e32 v39, v133
	v_lshlrev_b32_e32 v138, 16, v40
	v_and_b32_e32 v139, 0xffff0000, v40
	v_pk_mul_f32 v[56:57], v[56:57], v[138:139]
	v_lshlrev_b32_e32 v132, 16, v36
	v_and_b32_e32 v133, 0xffff0000, v36
	v_pk_mul_f32 v[132:133], v[38:39], v[132:133]
	v_cvt_pk_bf16_f32 v138, v56, v57
	v_exp_f32_e64 v56, -v134
	v_exp_f32_e64 v57, -v135
	v_cvt_pk_bf16_f32 v36, v132, v133
	v_lshlrev_b32_e32 v132, 16, v41
	v_and_b32_e32 v133, 0xffff0000, v41
	v_exp_f32_e32 v40, v134
	v_exp_f32_e32 v41, v135
	v_pk_mul_f32 v[56:57], v[56:57], v[132:133]
	v_lshlrev_b32_e32 v132, 16, v37
	v_and_b32_e32 v133, 0xffff0000, v37
	v_pk_mul_f32 v[132:133], v[40:41], v[132:133]
	v_cvt_pk_bf16_f32 v139, v56, v57
	v_cvt_pk_bf16_f32 v37, v132, v133
	ds_write_b128 v111, v[34:37]
	ds_write_b128 v111, v[136:139] offset:55296
	s_and_saveexec_b64 s[26:27], vcc
	s_cbranch_execz .LBB0_232
	ds_write_b128 v126, v[50:53] offset:46080
	ds_write_b128 v126, v[38:41] offset:46096
	s_branch .LBB0_232

	.amdhsa_kernel _Z10fwd_kernel4Args
		.amdhsa_group_segment_fixed_size 0
		.amdhsa_private_segment_fixed_size 0
		.amdhsa_kernarg_size 376
		.amdhsa_user_sgpr_count 2
		.amdhsa_user_sgpr_dispatch_ptr 0
		.amdhsa_user_sgpr_queue_ptr 0
		.amdhsa_user_sgpr_kernarg_segment_ptr 1
		.amdhsa_user_sgpr_dispatch_id 0
		.amdhsa_user_sgpr_kernarg_preload_length 0
		.amdhsa_user_sgpr_kernarg_preload_offset 0
		.amdhsa_user_sgpr_private_segment_size 0
		.amdhsa_uses_dynamic_stack 0
		.amdhsa_enable_private_segment 0
		.amdhsa_system_sgpr_workgroup_id_x 1
		.amdhsa_system_sgpr_workgroup_id_y 0
		.amdhsa_system_sgpr_workgroup_id_z 0
		.amdhsa_system_sgpr_workgroup_info 0
		.amdhsa_system_vgpr_workitem_id 0
		.amdhsa_next_free_vgpr 256
		.amdhsa_next_free_sgpr 102
		.amdhsa_accum_offset 256
		.amdhsa_reserve_vcc 1
		.amdhsa_float_round_mode_32 0
		.amdhsa_float_round_mode_16_64 0
		.amdhsa_float_denorm_mode_32 3
		.amdhsa_float_denorm_mode_16_64 3
		.amdhsa_dx10_clamp 1
		.amdhsa_ieee_mode 1
		.amdhsa_fp16_overflow 0
		.amdhsa_tg_split 0
		.amdhsa_exception_fp_ieee_invalid_op 0
		.amdhsa_exception_fp_denorm_src 0
		.amdhsa_exception_fp_ieee_div_zero 0
		.amdhsa_exception_fp_ieee_overflow 0
		.amdhsa_exception_fp_ieee_underflow 0
		.amdhsa_exception_fp_ieee_inexact 0
		.amdhsa_exception_int_div_zero 0
	.end_amdhsa_kernel

amdhsa.kernels:
  - .agpr_count:     0
    .args:
      - .offset:         0
        .size:           120
        .value_kind:     by_value
      - .offset:         120
        .size:           4
        .value_kind:     hidden_block_count_x
      - .offset:         124
        .size:           4
        .value_kind:     hidden_block_count_y
      - .offset:         128
        .size:           4
        .value_kind:     hidden_block_count_z
      - .offset:         132
        .size:           2
        .value_kind:     hidden_group_size_x
      - .offset:         134
        .size:           2
        .value_kind:     hidden_group_size_y
      - .offset:         136
        .size:           2
        .value_kind:     hidden_group_size_z
      - .offset:         138
        .size:           2
        .value_kind:     hidden_remainder_x
      - .offset:         140
        .size:           2
        .value_kind:     hidden_remainder_y
      - .offset:         142
        .size:           2
        .value_kind:     hidden_remainder_z
      - .offset:         160
        .size:           8
        .value_kind:     hidden_global_offset_x
      - .offset:         168
        .size:           8
        .value_kind:     hidden_global_offset_y
      - .offset:         176
        .size:           8
        .value_kind:     hidden_global_offset_z
      - .offset:         184
        .size:           2
        .value_kind:     hidden_grid_dims
      - .offset:         240
        .size:           4
        .value_kind:     hidden_dynamic_lds_size
    .group_segment_fixed_size: 0
    .kernarg_segment_align: 8
    .kernarg_segment_size: 376
    .language:       OpenCL C
    .language_version:
      - 2
      - 0
    .max_flat_workgroup_size: 512
    .name:           _Z10fwd_kernel4Args
    .private_segment_fixed_size: 0
    .sgpr_count:     108
    .sgpr_spill_count: 0
    .symbol:         _Z10fwd_kernel4Args.kd
    .uniform_work_group_size: 1
    .uses_dynamic_stack: false
    .vgpr_count:     256
    .vgpr_spill_count: 0
    .wavefront_size: 64
